# v50 + never-taken denormal-range guards around v_rsq removed in the P5/P6 epilogues (input is mean+eps >= 1e-6)
# speedup vs baseline: 1.0148x; 1.0040x over previous
; __device__ __forceinline__ unsigned pk2(float lo, float hi) { f32x2_t v = {lo, hi}; bf16x2_t b = __builtin_convertvector(v, bf16x2_t); return __builtin_bit_cast(unsigned, b); }
;     __device__ __forceinline__ void operator()(const f32x4 (&acc)[2][2][4][2], const Unit& u, int wr, int wc, int fr, int fq) const {
;         const int row0 = u.pm * BM + wr * 64 + fr, col0 = u.pn * BM + wc * 32 + 8 * fq;
;         f32x4 sp[2][4];
; #pragma unroll
;         for (int ai = 0; ai < 2; ++ai)
; #pragma unroll
;             for (int m = 0; m < 4; ++m) sp[ai][m] = *(const f32x4*)(ssq + (size_t)(row0 + ai * HALF + m * 16) * 16 + 4 * fq);
; #pragma unroll
;         for (int ai = 0; ai < 2; ++ai)
; #pragma unroll
;             for (int m = 0; m < 4; ++m) { const int row = row0 + ai * HALF + m * 16;
;                 float t = (sp[ai][m][0] + sp[ai][m][1]) + (sp[ai][m][2] + sp[ai][m][3]); t += __shfl_xor(t, 16); t += __shfl_xor(t, 32);
;                 const float rs = rsqrtf(t * (1.0f / DM) + EPS);
;                 bf16_t* rowp = O + (size_t)row * DFF + col0;
; #pragma unroll
;                 for (int bj = 0; bj < 2; ++bj) { f32x4 v0 = acc[ai][bj][m][0] * rs, v1 = acc[ai][bj][m][1] * rs;
; #pragma unroll
;                     for (int e = 0; e < 4; ++e) { v0[e] = fmaxf(v0[e], 0.f); v0[e] *= v0[e]; v1[e] = fmaxf(v1[e], 0.f); v1[e] *= v1[e]; }
;                     u32x4 w; w.x = pk2(v0[0], v0[1]); w.y = pk2(v0[2], v0[3]); w.z = pk2(v1[0], v1[1]); w.w = pk2(v1[2], v1[3]);
;                     *(u32x4*)(rowp + bj * HALF) = w; } }
;     }
.LBB0_894:
	s_lshl_b32 s15, s46, 8
	s_add_i32 s15, s15, s91
	v_mbcnt_lo_u32_b32 v128, -1, 0
	v_mbcnt_hi_u32_b32 v128, -1, v128
	v_and_b32_e32 v142, 64, v180
	v_ashrrev_i32_e32 v140, 4, v128
	v_and_or_b32 v136, v128, 15, s15
	v_lshlrev_b32_e32 v128, 2, v140
	v_or_b32_e32 v166, 16, v136
	v_ashrrev_i32_e32 v129, 31, v128
	v_ashrrev_i32_e32 v137, 31, v136
	v_ashrrev_i32_e32 v167, 31, v166
	v_lshl_add_u64 v[138:139], v[128:129], 2, s[10:11]
	v_lshlrev_b64 v[128:129], 6, v[136:137]
	v_lshlrev_b64 v[132:133], 6, v[166:167]
	v_lshl_add_u64 v[128:129], v[138:139], 0, v[128:129]
	v_lshl_add_u64 v[132:133], v[138:139], 0, v[132:133]
	global_load_dwordx4 v[128:131], v[128:129], off
	s_lshl_b32 s15, s44, 8
	global_load_dwordx4 v[132:135], v[132:133], off
	v_xor_b32_e32 v141, 16, v180
	v_add_u32_e32 v142, 64, v142
	s_or_b32 s15, s15, s78
	v_cmp_lt_i32_e32 vcc, v141, v142
	v_xor_b32_e32 v143, 32, v180
	v_lshl_add_u32 v140, v140, 3, s15
	v_cndmask_b32_e32 v141, v180, v141, vcc
	v_or_b32_e32 v164, 32, v136
	v_cmp_lt_i32_e32 vcc, v143, v142
	v_or_b32_e32 v162, 48, v136
	v_add_u32_e32 v160, 0x80, v136
	v_add_u32_e32 v158, 0x90, v136
	v_add_u32_e32 v156, 0xa0, v136
	v_add_u32_e32 v150, 0xb0, v136
	v_lshlrev_b32_e32 v181, 2, v141
	v_ashrrev_i32_e32 v141, 31, v140
	v_ashrrev_i32_e32 v165, 31, v164
	v_cndmask_b32_e32 v142, v180, v143, vcc
	v_ashrrev_i32_e32 v163, 31, v162
	v_ashrrev_i32_e32 v161, 31, v160
	v_ashrrev_i32_e32 v159, 31, v158
	v_ashrrev_i32_e32 v157, 31, v156
	v_ashrrev_i32_e32 v151, 31, v150
	v_lshlrev_b64 v[152:153], 1, v[140:141]
	v_lshlrev_b64 v[140:141], 6, v[164:165]
	v_lshlrev_b32_e32 v144, 2, v142
	v_lshlrev_b64 v[142:143], 6, v[162:163]
	v_lshlrev_b64 v[182:183], 6, v[160:161]
	v_lshlrev_b64 v[184:185], 6, v[158:159]
	v_lshlrev_b64 v[186:187], 6, v[156:157]
	v_lshlrev_b64 v[188:189], 6, v[150:151]
	v_lshl_add_u64 v[140:141], v[138:139], 0, v[140:141]
	v_lshl_add_u64 v[192:193], v[138:139], 0, v[186:187]
	v_lshl_add_u64 v[194:195], v[138:139], 0, v[188:189]
	v_mov_b64_e32 v[154:155], s[12:13]
	v_lshlrev_b64 v[136:137], 13, v[136:137]
	v_lshl_add_u64 v[136:137], s[36:37], 0, v[136:137]
	v_lshl_add_u64 v[196:197], v[136:137], 0, v[152:153]
	s_mov_b32 s44, s14
	s_mov_b32 s46, s26
	s_mov_b32 s20, s23
	s_mov_b64 s[50:51], s[42:43]
	s_mov_b64 s[48:49], s[40:41]
	s_waitcnt vmcnt(0)
	v_mov_b32_e32 v190, v129
	v_mov_b32_e32 v191, v130
	v_mov_b32_e32 v129, v131
	v_mov_b32_e32 v130, v133
	v_mov_b32_e32 v131, v134
	v_mov_b32_e32 v133, v135
	v_pk_add_f32 v[128:129], v[190:191], v[128:129]
	v_pk_add_f32 v[130:131], v[130:131], v[132:133]
	v_mov_b32_e32 v133, v128
	v_mov_b32_e32 v132, v130
	v_mov_b32_e32 v128, v131
	v_pk_add_f32 v[128:129], v[132:133], v[128:129]
	v_lshl_add_u64 v[132:133], v[138:139], 0, v[142:143]
	v_lshl_add_u64 v[134:135], v[138:139], 0, v[182:183]
	v_lshl_add_u64 v[190:191], v[138:139], 0, v[184:185]
	global_load_dwordx4 v[182:185], v[140:141], off
	global_load_dwordx4 v[186:189], v[132:133], off
	ds_bpermute_b32 v131, v181, v129
	ds_bpermute_b32 v130, v181, v128
	s_waitcnt lgkmcnt(0)
	v_pk_add_f32 v[128:129], v[128:129], v[130:131]
	ds_bpermute_b32 v131, v144, v129
	ds_bpermute_b32 v130, v144, v128
	s_waitcnt lgkmcnt(0)
	v_pk_add_f32 v[128:129], v[128:129], v[130:131]
	s_nop 0
	v_pk_fma_f32 v[198:199], v[128:129], s[8:9], v[154:155] op_sel_hi:[1,0,0]
	s_nop 0
	s_nop 1
	v_mov_b32_e32 v128, v199
	v_rsq_f32_e32 v199, v128
	global_load_dwordx4 v[140:143], v[134:135], off
	global_load_dwordx4 v[136:139], v[190:191], off
	s_nop 0
	global_load_dwordx4 v[132:135], v[192:193], off
	global_load_dwordx4 v[128:131], v[194:195], off
	v_mov_b32_e32 v190, v199
	v_pk_mul_f32 v[126:127], v[126:127], v[190:191] op_sel_hi:[1,0]
	v_pk_mul_f32 v[124:125], v[124:125], v[190:191] op_sel_hi:[1,0]
	v_pk_mul_f32 v[122:123], v[122:123], v[190:191] op_sel_hi:[1,0]
	v_pk_mul_f32 v[120:121], v[120:121], v[190:191] op_sel_hi:[1,0]
	v_pk_mul_f32 v[118:119], v[118:119], v[190:191] op_sel_hi:[1,0]
	v_pk_mul_f32 v[116:117], v[116:117], v[190:191] op_sel_hi:[1,0]
	v_pk_mul_f32 v[192:193], v[114:115], v[190:191] op_sel_hi:[1,0]
	v_pk_mul_f32 v[190:191], v[112:113], v[190:191] op_sel_hi:[1,0]
	v_max_f32_e32 v112, 0, v124
	v_max_f32_e32 v114, 0, v120
	v_max_f32_e32 v113, 0, v125
	v_max_f32_e32 v115, 0, v121
	v_max_f32_e32 v120, 0, v126
	v_max_f32_e32 v122, 0, v122
	v_max_f32_e32 v121, 0, v127
	v_max_f32_e32 v123, 0, v123
	v_pk_mul_f32 v[112:113], v[112:113], v[112:113]
	v_pk_mul_f32 v[114:115], v[114:115], v[114:115]
	v_pk_mul_f32 v[120:121], v[120:121], v[120:121]
	v_pk_mul_f32 v[122:123], v[122:123], v[122:123]
	v_cvt_pk_bf16_f32 v112, v112, v113
	v_cvt_pk_bf16_f32 v113, v120, v121
	v_cvt_pk_bf16_f32 v114, v114, v115
	v_cvt_pk_bf16_f32 v115, v122, v123
	v_max_f32_e32 v116, 0, v116
	global_store_dwordx4 v[196:197], v[112:115], off
	v_max_f32_e32 v117, 0, v117
	v_max_f32_e32 v112, 0, v190
	v_max_f32_e32 v113, 0, v191
	v_pk_mul_f32 v[114:115], v[116:117], v[116:117]
	v_pk_mul_f32 v[116:117], v[112:113], v[112:113]
	v_max_f32_e32 v112, 0, v118
	v_max_f32_e32 v113, 0, v119
	v_pk_mul_f32 v[120:121], v[112:113], v[112:113]
	v_cvt_pk_bf16_f32 v112, v114, v115
	v_mov_b32_e32 v114, v198
	v_cvt_pk_bf16_f32 v113, v120, v121
	v_rsq_f32_e32 v120, v114
	v_max_f32_e32 v118, 0, v192
	v_max_f32_e32 v119, 0, v193
	v_pk_mul_f32 v[118:119], v[118:119], v[118:119]
	v_cvt_pk_bf16_f32 v114, v116, v117
	v_cvt_pk_bf16_f32 v115, v118, v119
	global_store_dwordx4 v[196:197], v[112:115], off offset:256
	s_nop 1
	v_mov_b32_e32 v112, v120
	v_pk_mul_f32 v[104:105], v[104:105], v[112:113] op_sel_hi:[1,0]
	v_pk_mul_f32 v[110:111], v[110:111], v[112:113] op_sel_hi:[1,0]
	v_pk_mul_f32 v[108:109], v[108:109], v[112:113] op_sel_hi:[1,0]
	v_pk_mul_f32 v[106:107], v[106:107], v[112:113] op_sel_hi:[1,0]
	v_max_f32_e32 v104, 0, v104
	v_max_f32_e32 v105, 0, v105
	v_lshlrev_b64 v[114:115], 13, v[166:167]
	v_max_f32_e32 v108, 0, v108
	v_max_f32_e32 v109, 0, v109
	v_pk_mul_f32 v[116:117], v[104:105], v[104:105]
	v_max_f32_e32 v104, 0, v110
	v_max_f32_e32 v106, 0, v106
	v_max_f32_e32 v105, 0, v111
	v_max_f32_e32 v107, 0, v107
	v_lshl_add_u64 v[114:115], s[36:37], 0, v[114:115]
	v_pk_mul_f32 v[108:109], v[108:109], v[108:109]
	v_pk_mul_f32 v[110:111], v[104:105], v[104:105]
	v_pk_mul_f32 v[118:119], v[106:107], v[106:107]
	v_pk_mul_f32 v[96:97], v[96:97], v[112:113] op_sel_hi:[1,0]
	v_lshl_add_u64 v[114:115], v[114:115], 0, v[152:153]
	v_cvt_pk_bf16_f32 v104, v108, v109
	v_cvt_pk_bf16_f32 v105, v110, v111
	v_cvt_pk_bf16_f32 v106, v116, v117
	v_cvt_pk_bf16_f32 v107, v118, v119
	v_pk_mul_f32 v[102:103], v[102:103], v[112:113] op_sel_hi:[1,0]
	v_max_f32_e32 v96, 0, v96
	v_max_f32_e32 v97, 0, v97
	global_store_dwordx4 v[114:115], v[104:107], off
	v_pk_mul_f32 v[100:101], v[100:101], v[112:113] op_sel_hi:[1,0]
	v_pk_mul_f32 v[98:99], v[98:99], v[112:113] op_sel_hi:[1,0]
	v_pk_mul_f32 v[104:105], v[96:97], v[96:97]
	v_max_f32_e32 v96, 0, v102
	v_max_f32_e32 v97, 0, v103
	s_waitcnt vmcnt(8)
; __device__ __forceinline__ unsigned pk2(float lo, float hi) { f32x2_t v = {lo, hi}; bf16x2_t b = __builtin_convertvector(v, bf16x2_t); return __builtin_bit_cast(unsigned, b); }
;     __device__ __forceinline__ void operator()(const f32x4 (&acc)[2][2][4][2], const Unit& u, int wr, int wc, int fr, int fq) const {
;     ...
;             for (int m = 0; m < 4; ++m) { const int row = row0 + ai * HALF + m * 16;
;                 float t = (sp[ai][m][0] + sp[ai][m][1]) + (sp[ai][m][2] + sp[ai][m][3]); t += __shfl_xor(t, 16); t += __shfl_xor(t, 32);
;                 const float rs = rsqrtf(t * (1.0f / DM) + EPS);
;                 bf16_t* rowp = O + (size_t)row * DFF + col0;
; #pragma unroll
;                 for (int bj = 0; bj < 2; ++bj) { f32x4 v0 = acc[ai][bj][m][0] * rs, v1 = acc[ai][bj][m][1] * rs;
; #pragma unroll
;                     for (int e = 0; e < 4; ++e) { v0[e] = fmaxf(v0[e], 0.f); v0[e] *= v0[e]; v1[e] = fmaxf(v1[e], 0.f); v1[e] *= v1[e]; }
;                     u32x4 w; w.x = pk2(v0[0], v0[1]); w.y = pk2(v0[2], v0[3]); w.z = pk2(v1[0], v1[1]); w.w = pk2(v1[2], v1[3]);
;                     *(u32x4*)(rowp + bj * HALF) = w; } }
	v_mov_b32_e32 v102, v183
	v_mov_b32_e32 v103, v184
	v_mov_b32_e32 v183, v185
	s_waitcnt vmcnt(7)
	v_mov_b32_e32 v106, v187
	v_mov_b32_e32 v107, v188
	v_mov_b32_e32 v187, v189
	v_pk_add_f32 v[102:103], v[102:103], v[182:183]
	v_pk_add_f32 v[106:107], v[106:107], v[186:187]
	v_mov_b32_e32 v109, v102
	v_mov_b32_e32 v108, v106
	v_mov_b32_e32 v102, v107
	v_pk_add_f32 v[102:103], v[108:109], v[102:103]
	ds_bpermute_b32 v107, v181, v103
	ds_bpermute_b32 v106, v181, v102
	v_max_f32_e32 v100, 0, v100
	v_max_f32_e32 v101, 0, v101
	v_pk_mul_f32 v[100:101], v[100:101], v[100:101]
	v_pk_mul_f32 v[108:109], v[96:97], v[96:97]
	v_cvt_pk_bf16_f32 v96, v100, v101
	s_waitcnt lgkmcnt(0)
	v_pk_add_f32 v[100:101], v[102:103], v[106:107]
	ds_bpermute_b32 v103, v144, v101
	ds_bpermute_b32 v102, v144, v100
	v_max_f32_e32 v98, 0, v98
	v_max_f32_e32 v99, 0, v99
	v_pk_mul_f32 v[110:111], v[98:99], v[98:99]
	v_cvt_pk_bf16_f32 v97, v108, v109
	v_cvt_pk_bf16_f32 v98, v104, v105
	v_cvt_pk_bf16_f32 v99, v110, v111
	global_store_dwordx4 v[114:115], v[96:99], off offset:256
	s_waitcnt lgkmcnt(0)
	s_nop 0
	v_pk_add_f32 v[96:97], v[100:101], v[102:103]
	s_nop 0
	v_pk_fma_f32 v[96:97], v[96:97], s[8:9], v[154:155] op_sel_hi:[1,0,0]
	s_nop 0
	s_nop 1
	v_rsq_f32_e32 v97, v97
	v_lshlrev_b64 v[98:99], 13, v[164:165]
	v_lshl_add_u64 v[98:99], s[36:37], 0, v[98:99]
	v_lshl_add_u64 v[98:99], v[98:99], 0, v[152:153]
	v_mov_b32_e32 v100, v97
	v_pk_mul_f32 v[88:89], v[88:89], v[100:101] op_sel_hi:[1,0]
	v_pk_mul_f32 v[94:95], v[94:95], v[100:101] op_sel_hi:[1,0]
	v_pk_mul_f32 v[92:93], v[92:93], v[100:101] op_sel_hi:[1,0]
	v_pk_mul_f32 v[90:91], v[90:91], v[100:101] op_sel_hi:[1,0]
	v_max_f32_e32 v88, 0, v88
	v_max_f32_e32 v89, 0, v89
	v_max_f32_e32 v92, 0, v92
	v_max_f32_e32 v93, 0, v93
	v_pk_mul_f32 v[102:103], v[88:89], v[88:89]
	v_max_f32_e32 v88, 0, v94
	v_max_f32_e32 v90, 0, v90
	v_max_f32_e32 v89, 0, v95
	v_max_f32_e32 v91, 0, v91
	v_pk_mul_f32 v[92:93], v[92:93], v[92:93]
	v_pk_mul_f32 v[94:95], v[88:89], v[88:89]
	v_pk_mul_f32 v[104:105], v[90:91], v[90:91]
	v_pk_mul_f32 v[82:83], v[82:83], v[100:101] op_sel_hi:[1,0]
	v_cvt_pk_bf16_f32 v88, v92, v93
	v_cvt_pk_bf16_f32 v89, v94, v95
	v_cvt_pk_bf16_f32 v90, v102, v103
	v_cvt_pk_bf16_f32 v91, v104, v105
	v_pk_mul_f32 v[84:85], v[84:85], v[100:101] op_sel_hi:[1,0]
	v_pk_mul_f32 v[80:81], v[80:81], v[100:101] op_sel_hi:[1,0]
	v_max_f32_e32 v82, 0, v82
	v_max_f32_e32 v83, 0, v83
	global_store_dwordx4 v[98:99], v[88:91], off
	v_pk_mul_f32 v[86:87], v[86:87], v[100:101] op_sel_hi:[1,0]
	v_max_f32_e32 v84, 0, v84
	v_max_f32_e32 v80, 0, v80
	v_max_f32_e32 v85, 0, v85
	v_max_f32_e32 v81, 0, v81
	v_pk_mul_f32 v[90:91], v[82:83], v[82:83]
	v_pk_mul_f32 v[84:85], v[84:85], v[84:85]
	v_pk_mul_f32 v[88:89], v[80:81], v[80:81]
	v_max_f32_e32 v80, 0, v86
	v_max_f32_e32 v81, 0, v87
	v_mov_b32_e32 v82, v96
	v_pk_mul_f32 v[86:87], v[80:81], v[80:81]
	v_cvt_pk_bf16_f32 v80, v84, v85
	v_rsq_f32_e32 v84, v82
	v_cvt_pk_bf16_f32 v81, v86, v87
	v_cvt_pk_bf16_f32 v82, v88, v89
	v_cvt_pk_bf16_f32 v83, v90, v91
	global_store_dwordx4 v[98:99], v[80:83], off offset:256
	s_nop 1
	v_mov_b32_e32 v80, v84
	v_pk_mul_f32 v[72:73], v[72:73], v[80:81] op_sel_hi:[1,0]
	v_pk_mul_f32 v[78:79], v[78:79], v[80:81] op_sel_hi:[1,0]
	v_pk_mul_f32 v[76:77], v[76:77], v[80:81] op_sel_hi:[1,0]
	v_pk_mul_f32 v[74:75], v[74:75], v[80:81] op_sel_hi:[1,0]
	v_max_f32_e32 v72, 0, v72
	v_max_f32_e32 v73, 0, v73
	v_lshlrev_b64 v[82:83], 13, v[162:163]
	v_max_f32_e32 v76, 0, v76
	v_max_f32_e32 v77, 0, v77
	v_pk_mul_f32 v[84:85], v[72:73], v[72:73]
	v_max_f32_e32 v72, 0, v78
	v_max_f32_e32 v74, 0, v74
	v_max_f32_e32 v73, 0, v79
	v_max_f32_e32 v75, 0, v75
	v_lshl_add_u64 v[82:83], s[36:37], 0, v[82:83]
	v_pk_mul_f32 v[76:77], v[76:77], v[76:77]
	v_pk_mul_f32 v[78:79], v[72:73], v[72:73]
	v_pk_mul_f32 v[86:87], v[74:75], v[74:75]
	v_pk_mul_f32 v[64:65], v[64:65], v[80:81] op_sel_hi:[1,0]
	v_lshl_add_u64 v[82:83], v[82:83], 0, v[152:153]
	v_cvt_pk_bf16_f32 v72, v76, v77
	v_cvt_pk_bf16_f32 v73, v78, v79
	v_cvt_pk_bf16_f32 v74, v84, v85
	v_cvt_pk_bf16_f32 v75, v86, v87
	v_pk_mul_f32 v[70:71], v[70:71], v[80:81] op_sel_hi:[1,0]
	v_max_f32_e32 v64, 0, v64
	v_max_f32_e32 v65, 0, v65
	global_store_dwordx4 v[82:83], v[72:75], off
	v_pk_mul_f32 v[68:69], v[68:69], v[80:81] op_sel_hi:[1,0]
	v_pk_mul_f32 v[66:67], v[66:67], v[80:81] op_sel_hi:[1,0]
	v_pk_mul_f32 v[72:73], v[64:65], v[64:65]
	v_max_f32_e32 v64, 0, v70
	v_max_f32_e32 v65, 0, v71
	s_waitcnt vmcnt(10)
	v_mov_b32_e32 v70, v141
	v_mov_b32_e32 v71, v142
	v_mov_b32_e32 v141, v143
	s_waitcnt vmcnt(9)
	v_mov_b32_e32 v74, v137
	v_mov_b32_e32 v75, v138
	v_mov_b32_e32 v137, v139
	v_pk_add_f32 v[70:71], v[70:71], v[140:141]
	v_pk_add_f32 v[74:75], v[74:75], v[136:137]
	v_mov_b32_e32 v77, v70
	v_mov_b32_e32 v76, v74
	v_mov_b32_e32 v70, v75
	v_pk_add_f32 v[70:71], v[76:77], v[70:71]
	ds_bpermute_b32 v75, v181, v71
	ds_bpermute_b32 v74, v181, v70
	v_max_f32_e32 v68, 0, v68
	v_max_f32_e32 v69, 0, v69
	v_pk_mul_f32 v[68:69], v[68:69], v[68:69]
	v_pk_mul_f32 v[76:77], v[64:65], v[64:65]
	v_cvt_pk_bf16_f32 v64, v68, v69
	s_waitcnt lgkmcnt(0)
	v_pk_add_f32 v[68:69], v[70:71], v[74:75]
	ds_bpermute_b32 v71, v144, v69
	ds_bpermute_b32 v70, v144, v68
	v_max_f32_e32 v66, 0, v66
	v_max_f32_e32 v67, 0, v67
	v_pk_mul_f32 v[78:79], v[66:67], v[66:67]
	v_cvt_pk_bf16_f32 v65, v76, v77
	v_cvt_pk_bf16_f32 v66, v72, v73
	v_cvt_pk_bf16_f32 v67, v78, v79
	global_store_dwordx4 v[82:83], v[64:67], off offset:256
	s_waitcnt lgkmcnt(0)
; __device__ __forceinline__ unsigned pk2(float lo, float hi) { f32x2_t v = {lo, hi}; bf16x2_t b = __builtin_convertvector(v, bf16x2_t); return __builtin_bit_cast(unsigned, b); }
;     __device__ __forceinline__ void operator()(const f32x4 (&acc)[2][2][4][2], const Unit& u, int wr, int wc, int fr, int fq) const {
;     ...
;         for (int ai = 0; ai < 2; ++ai)
; #pragma unroll
;             for (int m = 0; m < 4; ++m) { const int row = row0 + ai * HALF + m * 16;
;                 float t = (sp[ai][m][0] + sp[ai][m][1]) + (sp[ai][m][2] + sp[ai][m][3]); t += __shfl_xor(t, 16); t += __shfl_xor(t, 32);
;                 const float rs = rsqrtf(t * (1.0f / DM) + EPS);
;                 bf16_t* rowp = O + (size_t)row * DFF + col0;
; #pragma unroll
;                 for (int bj = 0; bj < 2; ++bj) { f32x4 v0 = acc[ai][bj][m][0] * rs, v1 = acc[ai][bj][m][1] * rs;
; #pragma unroll
;                     for (int e = 0; e < 4; ++e) { v0[e] = fmaxf(v0[e], 0.f); v0[e] *= v0[e]; v1[e] = fmaxf(v1[e], 0.f); v1[e] *= v1[e]; }
;                     u32x4 w; w.x = pk2(v0[0], v0[1]); w.y = pk2(v0[2], v0[3]); w.z = pk2(v1[0], v1[1]); w.w = pk2(v1[2], v1[3]);
;                     *(u32x4*)(rowp + bj * HALF) = w; } }
	s_nop 0
	v_pk_add_f32 v[64:65], v[68:69], v[70:71]
	s_nop 0
	v_pk_fma_f32 v[64:65], v[64:65], s[8:9], v[154:155] op_sel_hi:[1,0,0]
	s_nop 0
	s_nop 1
	v_rsq_f32_e32 v65, v65
	v_lshlrev_b64 v[66:67], 13, v[160:161]
	v_lshl_add_u64 v[66:67], s[36:37], 0, v[66:67]
	v_lshl_add_u64 v[66:67], v[66:67], 0, v[152:153]
	v_mov_b32_e32 v68, v65
	v_pk_mul_f32 v[56:57], v[56:57], v[68:69] op_sel_hi:[1,0]
	v_pk_mul_f32 v[62:63], v[62:63], v[68:69] op_sel_hi:[1,0]
	v_pk_mul_f32 v[60:61], v[60:61], v[68:69] op_sel_hi:[1,0]
	v_pk_mul_f32 v[58:59], v[58:59], v[68:69] op_sel_hi:[1,0]
	v_max_f32_e32 v56, 0, v56
	v_max_f32_e32 v57, 0, v57
	v_max_f32_e32 v60, 0, v60
	v_max_f32_e32 v61, 0, v61
	v_pk_mul_f32 v[70:71], v[56:57], v[56:57]
	v_max_f32_e32 v56, 0, v62
	v_max_f32_e32 v58, 0, v58
	v_max_f32_e32 v57, 0, v63
	v_max_f32_e32 v59, 0, v59
	v_pk_mul_f32 v[60:61], v[60:61], v[60:61]
	v_pk_mul_f32 v[62:63], v[56:57], v[56:57]
	v_pk_mul_f32 v[72:73], v[58:59], v[58:59]
	v_pk_mul_f32 v[50:51], v[50:51], v[68:69] op_sel_hi:[1,0]
	v_cvt_pk_bf16_f32 v56, v60, v61
	v_cvt_pk_bf16_f32 v57, v62, v63
	v_cvt_pk_bf16_f32 v58, v70, v71
	v_cvt_pk_bf16_f32 v59, v72, v73
	v_pk_mul_f32 v[52:53], v[52:53], v[68:69] op_sel_hi:[1,0]
	v_pk_mul_f32 v[48:49], v[48:49], v[68:69] op_sel_hi:[1,0]
	v_max_f32_e32 v50, 0, v50
	v_max_f32_e32 v51, 0, v51
	global_store_dwordx4 v[66:67], v[56:59], off
	v_pk_mul_f32 v[54:55], v[54:55], v[68:69] op_sel_hi:[1,0]
	v_max_f32_e32 v52, 0, v52
	v_max_f32_e32 v48, 0, v48
	v_max_f32_e32 v53, 0, v53
	v_max_f32_e32 v49, 0, v49
	v_pk_mul_f32 v[58:59], v[50:51], v[50:51]
	v_pk_mul_f32 v[52:53], v[52:53], v[52:53]
	v_pk_mul_f32 v[56:57], v[48:49], v[48:49]
	v_max_f32_e32 v48, 0, v54
	v_max_f32_e32 v49, 0, v55
	v_mov_b32_e32 v50, v64
	v_pk_mul_f32 v[54:55], v[48:49], v[48:49]
	v_cvt_pk_bf16_f32 v48, v52, v53
	v_rsq_f32_e32 v52, v50
	v_cvt_pk_bf16_f32 v49, v54, v55
	v_cvt_pk_bf16_f32 v50, v56, v57
	v_cvt_pk_bf16_f32 v51, v58, v59
	global_store_dwordx4 v[66:67], v[48:51], off offset:256
	s_nop 1
	v_mov_b32_e32 v48, v52
	v_pk_mul_f32 v[40:41], v[40:41], v[48:49] op_sel_hi:[1,0]
	v_pk_mul_f32 v[46:47], v[46:47], v[48:49] op_sel_hi:[1,0]
	v_pk_mul_f32 v[44:45], v[44:45], v[48:49] op_sel_hi:[1,0]
	v_pk_mul_f32 v[42:43], v[42:43], v[48:49] op_sel_hi:[1,0]
	v_max_f32_e32 v40, 0, v40
	v_max_f32_e32 v41, 0, v41
	v_lshlrev_b64 v[50:51], 13, v[158:159]
	v_max_f32_e32 v44, 0, v44
	v_max_f32_e32 v45, 0, v45
	v_pk_mul_f32 v[52:53], v[40:41], v[40:41]
	v_max_f32_e32 v40, 0, v46
	v_max_f32_e32 v42, 0, v42
	v_max_f32_e32 v41, 0, v47
	v_max_f32_e32 v43, 0, v43
	v_lshl_add_u64 v[50:51], s[36:37], 0, v[50:51]
	v_pk_mul_f32 v[44:45], v[44:45], v[44:45]
	v_pk_mul_f32 v[46:47], v[40:41], v[40:41]
	v_pk_mul_f32 v[54:55], v[42:43], v[42:43]
	v_pk_mul_f32 v[32:33], v[32:33], v[48:49] op_sel_hi:[1,0]
	v_lshl_add_u64 v[50:51], v[50:51], 0, v[152:153]
	v_cvt_pk_bf16_f32 v40, v44, v45
	v_cvt_pk_bf16_f32 v41, v46, v47
	v_cvt_pk_bf16_f32 v42, v52, v53
	v_cvt_pk_bf16_f32 v43, v54, v55
	v_pk_mul_f32 v[38:39], v[38:39], v[48:49] op_sel_hi:[1,0]
	v_max_f32_e32 v32, 0, v32
	v_max_f32_e32 v33, 0, v33
	global_store_dwordx4 v[50:51], v[40:43], off
	v_pk_mul_f32 v[36:37], v[36:37], v[48:49] op_sel_hi:[1,0]
	v_pk_mul_f32 v[34:35], v[34:35], v[48:49] op_sel_hi:[1,0]
	v_pk_mul_f32 v[40:41], v[32:33], v[32:33]
	v_max_f32_e32 v32, 0, v38
	v_max_f32_e32 v33, 0, v39
	s_waitcnt vmcnt(12)
	v_mov_b32_e32 v38, v133
	v_mov_b32_e32 v39, v134
	v_mov_b32_e32 v133, v135
	s_waitcnt vmcnt(11)
	v_mov_b32_e32 v42, v129
	v_mov_b32_e32 v43, v130
	v_mov_b32_e32 v129, v131
	v_pk_add_f32 v[38:39], v[38:39], v[132:133]
	v_pk_add_f32 v[42:43], v[42:43], v[128:129]
	v_mov_b32_e32 v45, v38
	v_mov_b32_e32 v44, v42
	v_mov_b32_e32 v38, v43
	v_pk_add_f32 v[38:39], v[44:45], v[38:39]
	ds_bpermute_b32 v43, v181, v39
	ds_bpermute_b32 v42, v181, v38
	v_max_f32_e32 v36, 0, v36
	v_max_f32_e32 v37, 0, v37
	v_pk_mul_f32 v[36:37], v[36:37], v[36:37]
	v_pk_mul_f32 v[44:45], v[32:33], v[32:33]
	v_cvt_pk_bf16_f32 v32, v36, v37
	s_waitcnt lgkmcnt(0)
; __device__ __forceinline__ unsigned pk2(float lo, float hi) { f32x2_t v = {lo, hi}; bf16x2_t b = __builtin_convertvector(v, bf16x2_t); return __builtin_bit_cast(unsigned, b); }
;     __device__ __forceinline__ void operator()(const f32x4 (&acc)[2][2][4][2], const Unit& u, int wr, int wc, int fr, int fq) const {
;     ...
;         for (int ai = 0; ai < 2; ++ai)
; #pragma unroll
;             for (int m = 0; m < 4; ++m) { const int row = row0 + ai * HALF + m * 16;
;                 float t = (sp[ai][m][0] + sp[ai][m][1]) + (sp[ai][m][2] + sp[ai][m][3]); t += __shfl_xor(t, 16); t += __shfl_xor(t, 32);
;                 const float rs = rsqrtf(t * (1.0f / DM) + EPS);
;                 bf16_t* rowp = O + (size_t)row * DFF + col0;
; #pragma unroll
;                 for (int bj = 0; bj < 2; ++bj) { f32x4 v0 = acc[ai][bj][m][0] * rs, v1 = acc[ai][bj][m][1] * rs;
; #pragma unroll
;                     for (int e = 0; e < 4; ++e) { v0[e] = fmaxf(v0[e], 0.f); v0[e] *= v0[e]; v1[e] = fmaxf(v1[e], 0.f); v1[e] *= v1[e]; }
;                     u32x4 w; w.x = pk2(v0[0], v0[1]); w.y = pk2(v0[2], v0[3]); w.z = pk2(v1[0], v1[1]); w.w = pk2(v1[2], v1[3]);
;                     *(u32x4*)(rowp + bj * HALF) = w; } }
	v_pk_add_f32 v[36:37], v[38:39], v[42:43]
	ds_bpermute_b32 v39, v144, v37
	ds_bpermute_b32 v38, v144, v36
	v_max_f32_e32 v34, 0, v34
	v_max_f32_e32 v35, 0, v35
	v_pk_mul_f32 v[46:47], v[34:35], v[34:35]
	v_cvt_pk_bf16_f32 v33, v44, v45
	v_cvt_pk_bf16_f32 v34, v40, v41
	v_cvt_pk_bf16_f32 v35, v46, v47
	global_store_dwordx4 v[50:51], v[32:35], off offset:256
	s_waitcnt lgkmcnt(0)
	s_nop 0
	v_pk_add_f32 v[32:33], v[36:37], v[38:39]
	s_nop 0
	v_pk_fma_f32 v[32:33], v[32:33], s[8:9], v[154:155] op_sel_hi:[1,0,0]
	s_nop 0
	s_nop 1
	v_rsq_f32_e32 v33, v33
	v_lshlrev_b64 v[34:35], 13, v[156:157]
	v_lshl_add_u64 v[34:35], s[36:37], 0, v[34:35]
	v_lshl_add_u64 v[34:35], v[34:35], 0, v[152:153]
	v_mov_b32_e32 v36, v33
	v_pk_mul_f32 v[24:25], v[24:25], v[36:37] op_sel_hi:[1,0]
	v_pk_mul_f32 v[30:31], v[30:31], v[36:37] op_sel_hi:[1,0]
	v_pk_mul_f32 v[28:29], v[28:29], v[36:37] op_sel_hi:[1,0]
	v_pk_mul_f32 v[26:27], v[26:27], v[36:37] op_sel_hi:[1,0]
	v_max_f32_e32 v24, 0, v24
	v_max_f32_e32 v25, 0, v25
	v_max_f32_e32 v28, 0, v28
	v_max_f32_e32 v29, 0, v29
	v_pk_mul_f32 v[38:39], v[24:25], v[24:25]
	v_max_f32_e32 v24, 0, v30
	v_max_f32_e32 v26, 0, v26
	v_max_f32_e32 v25, 0, v31
	v_max_f32_e32 v27, 0, v27
	v_pk_mul_f32 v[28:29], v[28:29], v[28:29]
	v_pk_mul_f32 v[30:31], v[24:25], v[24:25]
	v_pk_mul_f32 v[40:41], v[26:27], v[26:27]
	v_pk_mul_f32 v[18:19], v[18:19], v[36:37] op_sel_hi:[1,0]
	v_cvt_pk_bf16_f32 v24, v28, v29
	v_cvt_pk_bf16_f32 v25, v30, v31
	v_cvt_pk_bf16_f32 v26, v38, v39
	v_cvt_pk_bf16_f32 v27, v40, v41
	v_pk_mul_f32 v[20:21], v[20:21], v[36:37] op_sel_hi:[1,0]
	v_pk_mul_f32 v[16:17], v[16:17], v[36:37] op_sel_hi:[1,0]
	v_max_f32_e32 v18, 0, v18
	v_max_f32_e32 v19, 0, v19
	global_store_dwordx4 v[34:35], v[24:27], off
	v_pk_mul_f32 v[22:23], v[22:23], v[36:37] op_sel_hi:[1,0]
	v_max_f32_e32 v20, 0, v20
	v_max_f32_e32 v16, 0, v16
	v_max_f32_e32 v21, 0, v21
	v_max_f32_e32 v17, 0, v17
	v_pk_mul_f32 v[26:27], v[18:19], v[18:19]
	v_pk_mul_f32 v[20:21], v[20:21], v[20:21]
	v_pk_mul_f32 v[24:25], v[16:17], v[16:17]
	v_max_f32_e32 v16, 0, v22
	v_max_f32_e32 v17, 0, v23
	v_mov_b32_e32 v18, v32
	v_pk_mul_f32 v[22:23], v[16:17], v[16:17]
	v_cvt_pk_bf16_f32 v16, v20, v21
	v_rsq_f32_e32 v20, v18
	v_cvt_pk_bf16_f32 v17, v22, v23
	v_cvt_pk_bf16_f32 v18, v24, v25
	v_cvt_pk_bf16_f32 v19, v26, v27
	global_store_dwordx4 v[34:35], v[16:19], off offset:256
	s_nop 1
	v_mov_b32_e32 v16, v20
	v_pk_mul_f32 v[8:9], v[8:9], v[16:17] op_sel_hi:[1,0]
	v_pk_mul_f32 v[14:15], v[14:15], v[16:17] op_sel_hi:[1,0]
	v_pk_mul_f32 v[12:13], v[12:13], v[16:17] op_sel_hi:[1,0]
	v_pk_mul_f32 v[10:11], v[10:11], v[16:17] op_sel_hi:[1,0]
	v_max_f32_e32 v8, 0, v8
	v_max_f32_e32 v9, 0, v9
	v_lshlrev_b64 v[18:19], 13, v[150:151]
	v_max_f32_e32 v12, 0, v12
	v_max_f32_e32 v13, 0, v13
	v_pk_mul_f32 v[20:21], v[8:9], v[8:9]
	v_max_f32_e32 v8, 0, v14
	v_max_f32_e32 v10, 0, v10
	v_max_f32_e32 v9, 0, v15
	v_max_f32_e32 v11, 0, v11
	v_lshl_add_u64 v[18:19], s[36:37], 0, v[18:19]
	v_pk_mul_f32 v[12:13], v[12:13], v[12:13]
	v_pk_mul_f32 v[14:15], v[8:9], v[8:9]
	v_pk_mul_f32 v[22:23], v[10:11], v[10:11]
	v_pk_mul_f32 v[0:1], v[0:1], v[16:17] op_sel_hi:[1,0]
	v_lshl_add_u64 v[18:19], v[18:19], 0, v[152:153]
	v_cvt_pk_bf16_f32 v8, v12, v13
	v_cvt_pk_bf16_f32 v9, v14, v15
	v_cvt_pk_bf16_f32 v10, v20, v21
	v_cvt_pk_bf16_f32 v11, v22, v23
	v_pk_mul_f32 v[6:7], v[6:7], v[16:17] op_sel_hi:[1,0]
	v_pk_mul_f32 v[4:5], v[4:5], v[16:17] op_sel_hi:[1,0]
	v_pk_mul_f32 v[2:3], v[2:3], v[16:17] op_sel_hi:[1,0]
	v_max_f32_e32 v0, 0, v0
	v_max_f32_e32 v1, 0, v1
	global_store_dwordx4 v[18:19], v[8:11], off
	v_max_f32_e32 v4, 0, v4
	v_max_f32_e32 v5, 0, v5
	v_pk_mul_f32 v[8:9], v[0:1], v[0:1]
	v_max_f32_e32 v0, 0, v6
	v_max_f32_e32 v2, 0, v2
	v_max_f32_e32 v1, 0, v7
	v_max_f32_e32 v3, 0, v3
	v_pk_mul_f32 v[4:5], v[4:5], v[4:5]
	v_pk_mul_f32 v[6:7], v[0:1], v[0:1]
	v_pk_mul_f32 v[10:11], v[2:3], v[2:3]
	v_cvt_pk_bf16_f32 v0, v4, v5
	v_cvt_pk_bf16_f32 v1, v6, v7
	v_cvt_pk_bf16_f32 v2, v8, v9
	v_cvt_pk_bf16_f32 v3, v10, v11
	s_and_b64 vcc, exec, s[4:5]
	global_store_dwordx4 v[18:19], v[0:3], off offset:256
	s_cbranch_vccnz .LBB0_900

;     __device__ __forceinline__ void operator()(f32x4 (&acc)[2][2][4][2], const Unit& u, int wr, int wc, int fr, int fq) const {
;     ...
; #pragma unroll
;         for (int ai = 0; ai < 2; ++ai)
; #pragma unroll
;             for (int m = 0; m < 4; ++m) { const int row = row0 + ai * HALF + m * 16; float* orow = out + (size_t)row * DM + col0;
;                 const unsigned long long* sp = (const unsigned long long*)(xbuf + (size_t)row * 16 + 4 * fq);
;                 const unsigned long long qa = __hip_atomic_load(sp, __ATOMIC_RELAXED, __HIP_MEMORY_SCOPE_AGENT), qb = __hip_atomic_load(sp + 1, __ATOMIC_RELAXED, __HIP_MEMORY_SCOPE_AGENT);
;                 float t = (__uint_as_float((unsigned)qa) + __uint_as_float((unsigned)(qa >> 32))) + (__uint_as_float((unsigned)qb) + __uint_as_float((unsigned)(qb >> 32)));
;                 t += __shfl_xor(t, 16); t += __shfl_xor(t, 32);
;                 const float rs = rsqrtf(t * (1.0f / DM) + EPS);
; #pragma unroll
;                 for (int bj = 0; bj < 2; ++bj)
; #pragma unroll
;                     for (int n = 0; n < 2; ++n) { const int co = bj * HALF + n * 16; const f32x4 g = *(const f32x4*)(gf + col0 + co); *(f32x4*)(orow + co) = acc[ai][bj][m][n] * rs * g; } }
.LBB0_994:
	v_ashrrev_i32_e32 v139, 31, v138
	v_lshlrev_b64 v[170:171], 2, v[138:139]
	v_lshl_add_u64 v[138:139], v[144:145], 0, v[170:171]
	global_load_dwordx2 v[144:145], v[138:139], off sc1
	global_load_dwordx2 v[190:191], v[138:139], off offset:8 sc1
	v_readlane_b32 s56, v249, 49
	v_readlane_b32 s58, v249, 51
	v_readlane_b32 s59, v249, 52
	v_lshlrev_b64 v[138:139], 2, v[136:137]
	s_mov_b64 s[46:47], s[58:59]
	v_lshl_add_u64 v[136:137], s[46:47], 0, v[138:139]
	global_load_dwordx4 v[212:215], v[136:137], off
	global_load_dwordx4 v[216:219], v[136:137], off offset:64
	global_load_dwordx4 v[220:223], v[136:137], off offset:512
	global_load_dwordx4 v[224:227], v[136:137], off offset:576
	v_readlane_b32 s60, v249, 53
	v_readlane_b32 s61, v249, 54
	s_mov_b64 s[48:49], s[60:61]
	v_lshlrev_b64 v[134:135], 12, v[134:135]
	v_lshl_add_u64 v[134:135], s[48:49], 0, v[134:135]
	v_lshl_add_u64 v[134:135], v[134:135], 0, v[138:139]
	v_lshlrev_b64 v[100:101], 12, v[100:101]
	v_lshl_add_u64 v[100:101], s[48:49], 0, v[100:101]
	v_lshl_add_u64 v[100:101], v[100:101], 0, v[138:139]
	v_lshlrev_b64 v[84:85], 12, v[84:85]
	v_lshl_add_u64 v[84:85], s[48:49], 0, v[84:85]
	v_lshl_add_u64 v[84:85], v[84:85], 0, v[138:139]
	v_lshlrev_b64 v[68:69], 12, v[68:69]
	v_lshl_add_u64 v[68:69], s[48:49], 0, v[68:69]
	v_lshl_add_u64 v[68:69], v[68:69], 0, v[138:139]
	v_lshlrev_b64 v[52:53], 12, v[52:53]
	v_lshl_add_u64 v[52:53], s[48:49], 0, v[52:53]
	v_lshl_add_u64 v[52:53], v[52:53], 0, v[138:139]
	v_lshlrev_b64 v[36:37], 12, v[36:37]
	v_lshl_add_u64 v[36:37], s[48:49], 0, v[36:37]
	v_lshl_add_u64 v[36:37], v[36:37], 0, v[138:139]
	v_lshlrev_b64 v[20:21], 12, v[20:21]
	v_lshl_add_u64 v[20:21], s[48:49], 0, v[20:21]
	v_lshl_add_u64 v[20:21], v[20:21], 0, v[138:139]
	v_readlane_b32 s57, v249, 50
	v_readlane_b32 s62, v249, 55
	v_readlane_b32 s63, v249, 56
	s_waitcnt vmcnt(5)
	v_add_f32_e32 v144, v144, v145
	s_waitcnt vmcnt(4)
	v_add_f32_e32 v145, v190, v191
	v_add_f32_e32 v144, v144, v145
	ds_bpermute_b32 v145, v128, v144
	s_waitcnt lgkmcnt(0)
	v_add_f32_e32 v144, v144, v145
	ds_bpermute_b32 v145, v184, v144
	s_waitcnt lgkmcnt(0)
	v_add_f32_e32 v144, v144, v145
	v_fmamk_f32 v144, v144, 0x3a800000, v183
	s_nop 1
	v_rsq_f32_e32 v144, v144
	s_nop 0
	v_pk_mul_f32 v[140:141], v[140:141], v[144:145] op_sel_hi:[1,0]
	v_pk_mul_f32 v[126:127], v[126:127], v[144:145] op_sel_hi:[1,0]
	s_waitcnt vmcnt(0)
	s_nop 1
	v_mov_b64_e32 v[186:187], v[212:213]
	v_mov_b64_e32 v[188:189], v[214:215]
	v_pk_mul_f32 v[186:187], v[186:187], v[140:141]
	v_pk_mul_f32 v[188:189], v[188:189], v[126:127]
	global_store_dwordx4 v[134:135], v[186:189], off
	s_nop 1
	v_mov_b64_e32 v[186:187], v[216:217]
	v_mov_b64_e32 v[188:189], v[218:219]
	v_pk_mul_f32 v[126:127], v[122:123], v[144:145] op_sel_hi:[1,0]
	v_pk_mul_f32 v[122:123], v[124:125], v[144:145] op_sel_hi:[1,0]
	v_pk_mul_f32 v[118:119], v[118:119], v[144:145] op_sel_hi:[1,0]
	v_pk_mul_f32 v[116:117], v[116:117], v[144:145] op_sel_hi:[1,0]
	v_pk_mul_f32 v[114:115], v[114:115], v[144:145] op_sel_hi:[1,0]
	v_pk_mul_f32 v[112:113], v[112:113], v[144:145] op_sel_hi:[1,0]
	v_pk_mul_f32 v[122:123], v[186:187], v[122:123]
	v_pk_mul_f32 v[124:125], v[188:189], v[126:127]
	global_store_dwordx4 v[134:135], v[122:125], off offset:64
	s_nop 1
	v_mov_b64_e32 v[122:123], v[220:221]
	v_mov_b64_e32 v[124:125], v[222:223]
	v_pk_mul_f32 v[116:117], v[122:123], v[116:117]
	v_pk_mul_f32 v[118:119], v[124:125], v[118:119]
	global_store_dwordx4 v[134:135], v[116:119], off offset:512
	s_nop 1
	v_mov_b64_e32 v[116:117], v[224:225]
	v_mov_b64_e32 v[118:119], v[226:227]
	v_lshl_add_u64 v[122:123], v[148:149], 0, v[170:171]
	v_pk_mul_f32 v[112:113], v[116:117], v[112:113]
	v_pk_mul_f32 v[114:115], v[118:119], v[114:115]
	global_store_dwordx4 v[134:135], v[112:115], off offset:576
	global_load_dwordx2 v[116:117], v[122:123], off sc1
	global_load_dwordx2 v[118:119], v[122:123], off offset:8 sc1
	s_nop 0
	s_nop 1
	v_mov_b64_e32 v[112:113], v[212:213]
	v_mov_b64_e32 v[114:115], v[214:215]
	s_waitcnt vmcnt(1)
	v_add_f32_e32 v116, v116, v117
	s_waitcnt vmcnt(0)
	v_add_f32_e32 v117, v118, v119
	v_add_f32_e32 v116, v116, v117
	ds_bpermute_b32 v117, v128, v116
	s_waitcnt lgkmcnt(0)
	v_add_f32_e32 v116, v116, v117
	ds_bpermute_b32 v117, v184, v116
	s_waitcnt lgkmcnt(0)
	v_add_f32_e32 v116, v116, v117
	v_fmamk_f32 v116, v116, 0x3a800000, v183
	s_nop 1
	v_rsq_f32_e32 v118, v116
	v_lshlrev_b64 v[116:117], 12, v[120:121]
	v_lshl_add_u64 v[116:117], s[48:49], 0, v[116:117]
	v_lshl_add_u64 v[116:117], v[116:117], 0, v[138:139]
	v_pk_mul_f32 v[120:121], v[142:143], v[118:119] op_sel_hi:[1,0]
	v_pk_mul_f32 v[110:111], v[110:111], v[118:119] op_sel_hi:[1,0]
	v_pk_mul_f32 v[112:113], v[112:113], v[120:121]
	v_pk_mul_f32 v[114:115], v[114:115], v[110:111]
	global_store_dwordx4 v[116:117], v[112:115], off
	s_nop 1
	v_mov_b64_e32 v[110:111], v[216:217]
	v_mov_b64_e32 v[112:113], v[218:219]
	v_pk_mul_f32 v[98:99], v[98:99], v[118:119] op_sel_hi:[1,0]
	v_pk_mul_f32 v[114:115], v[106:107], v[118:119] op_sel_hi:[1,0]
	v_pk_mul_f32 v[106:107], v[108:109], v[118:119] op_sel_hi:[1,0]
	v_pk_mul_f32 v[96:97], v[96:97], v[118:119] op_sel_hi:[1,0]
	v_pk_mul_f32 v[106:107], v[110:111], v[106:107]
	v_pk_mul_f32 v[108:109], v[112:113], v[114:115]
	global_store_dwordx4 v[116:117], v[106:109], off offset:64
	s_nop 1
	v_mov_b64_e32 v[106:107], v[220:221]
	v_mov_b64_e32 v[108:109], v[222:223]
	v_pk_mul_f32 v[110:111], v[102:103], v[118:119] op_sel_hi:[1,0]
	v_pk_mul_f32 v[102:103], v[104:105], v[118:119] op_sel_hi:[1,0]
	v_pk_mul_f32 v[104:105], v[108:109], v[110:111]
	v_pk_mul_f32 v[102:103], v[106:107], v[102:103]
	global_store_dwordx4 v[116:117], v[102:105], off offset:512
	s_nop 1
	v_mov_b64_e32 v[102:103], v[224:225]
	v_mov_b64_e32 v[104:105], v[226:227]
	v_lshl_add_u64 v[106:107], v[152:153], 0, v[170:171]
	v_pk_mul_f32 v[96:97], v[102:103], v[96:97]
	v_pk_mul_f32 v[98:99], v[104:105], v[98:99]
	global_store_dwordx4 v[116:117], v[96:99], off offset:576
	global_load_dwordx2 v[102:103], v[106:107], off sc1
	global_load_dwordx2 v[104:105], v[106:107], off offset:8 sc1
	s_nop 0
	s_nop 1
	v_mov_b64_e32 v[96:97], v[212:213]
	v_mov_b64_e32 v[98:99], v[214:215]
	s_waitcnt vmcnt(1)
;     __device__ __forceinline__ void operator()(f32x4 (&acc)[2][2][4][2], const Unit& u, int wr, int wc, int fr, int fq) const {
;     ...
;             for (int m = 0; m < 4; ++m) { const int row = row0 + ai * HALF + m * 16; float* orow = out + (size_t)row * DM + col0;
;                 const unsigned long long* sp = (const unsigned long long*)(xbuf + (size_t)row * 16 + 4 * fq);
;                 const unsigned long long qa = __hip_atomic_load(sp, __ATOMIC_RELAXED, __HIP_MEMORY_SCOPE_AGENT), qb = __hip_atomic_load(sp + 1, __ATOMIC_RELAXED, __HIP_MEMORY_SCOPE_AGENT);
;                 float t = (__uint_as_float((unsigned)qa) + __uint_as_float((unsigned)(qa >> 32))) + (__uint_as_float((unsigned)qb) + __uint_as_float((unsigned)(qb >> 32)));
;                 t += __shfl_xor(t, 16); t += __shfl_xor(t, 32);
;                 const float rs = rsqrtf(t * (1.0f / DM) + EPS);
; #pragma unroll
;                 for (int bj = 0; bj < 2; ++bj)
; #pragma unroll
;                     for (int n = 0; n < 2; ++n) { const int co = bj * HALF + n * 16; const f32x4 g = *(const f32x4*)(gf + col0 + co); *(f32x4*)(orow + co) = acc[ai][bj][m][n] * rs * g; } }
	v_add_f32_e32 v102, v102, v103
	s_waitcnt vmcnt(0)
	v_add_f32_e32 v103, v104, v105
	v_add_f32_e32 v102, v102, v103
	ds_bpermute_b32 v103, v128, v102
	s_waitcnt lgkmcnt(0)
	v_add_f32_e32 v102, v102, v103
	ds_bpermute_b32 v103, v184, v102
	s_waitcnt lgkmcnt(0)
	v_add_f32_e32 v102, v102, v103
	v_fmamk_f32 v102, v102, 0x3a800000, v183
	s_nop 1
	v_rsq_f32_e32 v102, v102
	s_nop 0
	v_pk_mul_f32 v[104:105], v[146:147], v[102:103] op_sel_hi:[1,0]
	v_pk_mul_f32 v[94:95], v[94:95], v[102:103] op_sel_hi:[1,0]
	v_pk_mul_f32 v[96:97], v[96:97], v[104:105]
	v_pk_mul_f32 v[98:99], v[98:99], v[94:95]
	global_store_dwordx4 v[100:101], v[96:99], off
	s_nop 1
	v_mov_b64_e32 v[94:95], v[216:217]
	v_mov_b64_e32 v[96:97], v[218:219]
	v_pk_mul_f32 v[82:83], v[82:83], v[102:103] op_sel_hi:[1,0]
	v_pk_mul_f32 v[98:99], v[90:91], v[102:103] op_sel_hi:[1,0]
	v_pk_mul_f32 v[90:91], v[92:93], v[102:103] op_sel_hi:[1,0]
	v_pk_mul_f32 v[80:81], v[80:81], v[102:103] op_sel_hi:[1,0]
	v_pk_mul_f32 v[90:91], v[94:95], v[90:91]
	v_pk_mul_f32 v[92:93], v[96:97], v[98:99]
	global_store_dwordx4 v[100:101], v[90:93], off offset:64
	s_nop 1
	v_mov_b64_e32 v[90:91], v[220:221]
	v_mov_b64_e32 v[92:93], v[222:223]
	v_pk_mul_f32 v[94:95], v[86:87], v[102:103] op_sel_hi:[1,0]
	v_pk_mul_f32 v[86:87], v[88:89], v[102:103] op_sel_hi:[1,0]
	v_pk_mul_f32 v[88:89], v[92:93], v[94:95]
	v_pk_mul_f32 v[86:87], v[90:91], v[86:87]
	global_store_dwordx4 v[100:101], v[86:89], off offset:512
	s_nop 1
	v_mov_b64_e32 v[86:87], v[224:225]
	v_mov_b64_e32 v[88:89], v[226:227]
	v_lshl_add_u64 v[90:91], v[156:157], 0, v[170:171]
	v_pk_mul_f32 v[80:81], v[86:87], v[80:81]
	v_pk_mul_f32 v[82:83], v[88:89], v[82:83]
	global_store_dwordx4 v[100:101], v[80:83], off offset:576
	global_load_dwordx2 v[86:87], v[90:91], off sc1
	global_load_dwordx2 v[88:89], v[90:91], off offset:8 sc1
	s_nop 0
	s_nop 1
	v_mov_b64_e32 v[80:81], v[212:213]
	v_mov_b64_e32 v[82:83], v[214:215]
	s_waitcnt vmcnt(1)
	v_add_f32_e32 v86, v86, v87
	s_waitcnt vmcnt(0)
	v_add_f32_e32 v87, v88, v89
	v_add_f32_e32 v86, v86, v87
	ds_bpermute_b32 v87, v128, v86
	s_waitcnt lgkmcnt(0)
	v_add_f32_e32 v86, v86, v87
	ds_bpermute_b32 v87, v184, v86
	s_waitcnt lgkmcnt(0)
	v_add_f32_e32 v86, v86, v87
	v_fmamk_f32 v86, v86, 0x3a800000, v183
	s_nop 1
	v_rsq_f32_e32 v86, v86
	s_nop 0
	v_pk_mul_f32 v[88:89], v[150:151], v[86:87] op_sel_hi:[1,0]
	v_pk_mul_f32 v[78:79], v[78:79], v[86:87] op_sel_hi:[1,0]
	v_pk_mul_f32 v[80:81], v[80:81], v[88:89]
	v_pk_mul_f32 v[82:83], v[82:83], v[78:79]
	global_store_dwordx4 v[84:85], v[80:83], off
	s_nop 1
	v_mov_b64_e32 v[78:79], v[216:217]
	v_mov_b64_e32 v[80:81], v[218:219]
	v_pk_mul_f32 v[66:67], v[66:67], v[86:87] op_sel_hi:[1,0]
	v_pk_mul_f32 v[82:83], v[74:75], v[86:87] op_sel_hi:[1,0]
	v_pk_mul_f32 v[74:75], v[76:77], v[86:87] op_sel_hi:[1,0]
	v_pk_mul_f32 v[64:65], v[64:65], v[86:87] op_sel_hi:[1,0]
	v_pk_mul_f32 v[74:75], v[78:79], v[74:75]
	v_pk_mul_f32 v[76:77], v[80:81], v[82:83]
	global_store_dwordx4 v[84:85], v[74:77], off offset:64
	s_nop 1
	v_mov_b64_e32 v[74:75], v[220:221]
	v_mov_b64_e32 v[76:77], v[222:223]
	v_pk_mul_f32 v[78:79], v[70:71], v[86:87] op_sel_hi:[1,0]
	v_pk_mul_f32 v[70:71], v[72:73], v[86:87] op_sel_hi:[1,0]
	v_pk_mul_f32 v[72:73], v[76:77], v[78:79]
	v_pk_mul_f32 v[70:71], v[74:75], v[70:71]
	global_store_dwordx4 v[84:85], v[70:73], off offset:512
	s_nop 1
	v_mov_b64_e32 v[70:71], v[224:225]
	v_mov_b64_e32 v[72:73], v[226:227]
	v_lshl_add_u64 v[74:75], v[160:161], 0, v[170:171]
	v_pk_mul_f32 v[64:65], v[70:71], v[64:65]
	v_pk_mul_f32 v[66:67], v[72:73], v[66:67]
	global_store_dwordx4 v[84:85], v[64:67], off offset:576
	global_load_dwordx2 v[70:71], v[74:75], off sc1
	global_load_dwordx2 v[72:73], v[74:75], off offset:8 sc1
	s_nop 0
	s_nop 1
	v_mov_b64_e32 v[64:65], v[212:213]
	v_mov_b64_e32 v[66:67], v[214:215]
	s_waitcnt vmcnt(1)
	v_add_f32_e32 v70, v70, v71
	s_waitcnt vmcnt(0)
	v_add_f32_e32 v71, v72, v73
	v_add_f32_e32 v70, v70, v71
	ds_bpermute_b32 v71, v128, v70
	s_waitcnt lgkmcnt(0)
	v_add_f32_e32 v70, v70, v71
	ds_bpermute_b32 v71, v184, v70
	s_waitcnt lgkmcnt(0)
	v_add_f32_e32 v70, v70, v71
	v_fmamk_f32 v70, v70, 0x3a800000, v183
	s_nop 1
	v_rsq_f32_e32 v70, v70
	s_nop 0
	v_pk_mul_f32 v[72:73], v[154:155], v[70:71] op_sel_hi:[1,0]
	v_pk_mul_f32 v[62:63], v[62:63], v[70:71] op_sel_hi:[1,0]
	v_pk_mul_f32 v[64:65], v[64:65], v[72:73]
	v_pk_mul_f32 v[66:67], v[66:67], v[62:63]
	global_store_dwordx4 v[68:69], v[64:67], off
	s_nop 1
	v_mov_b64_e32 v[62:63], v[216:217]
	v_mov_b64_e32 v[64:65], v[218:219]
	v_pk_mul_f32 v[50:51], v[50:51], v[70:71] op_sel_hi:[1,0]
	v_pk_mul_f32 v[66:67], v[58:59], v[70:71] op_sel_hi:[1,0]
	v_pk_mul_f32 v[58:59], v[60:61], v[70:71] op_sel_hi:[1,0]
	v_pk_mul_f32 v[48:49], v[48:49], v[70:71] op_sel_hi:[1,0]
	v_pk_mul_f32 v[58:59], v[62:63], v[58:59]
	v_pk_mul_f32 v[60:61], v[64:65], v[66:67]
	global_store_dwordx4 v[68:69], v[58:61], off offset:64
	s_nop 1
	v_mov_b64_e32 v[58:59], v[220:221]
	v_mov_b64_e32 v[60:61], v[222:223]
	v_pk_mul_f32 v[62:63], v[54:55], v[70:71] op_sel_hi:[1,0]
	v_pk_mul_f32 v[54:55], v[56:57], v[70:71] op_sel_hi:[1,0]
	v_pk_mul_f32 v[56:57], v[60:61], v[62:63]
	v_pk_mul_f32 v[54:55], v[58:59], v[54:55]
	global_store_dwordx4 v[68:69], v[54:57], off offset:512
	s_nop 1
	v_mov_b64_e32 v[54:55], v[224:225]
	v_mov_b64_e32 v[56:57], v[226:227]
	v_lshl_add_u64 v[58:59], v[164:165], 0, v[170:171]
	v_pk_mul_f32 v[48:49], v[54:55], v[48:49]
	v_pk_mul_f32 v[50:51], v[56:57], v[50:51]
	global_store_dwordx4 v[68:69], v[48:51], off offset:576
	global_load_dwordx2 v[54:55], v[58:59], off sc1
	global_load_dwordx2 v[56:57], v[58:59], off offset:8 sc1
	s_nop 0
	s_nop 1
	v_mov_b64_e32 v[48:49], v[212:213]
	v_mov_b64_e32 v[50:51], v[214:215]
	s_waitcnt vmcnt(1)
; #define PG8_BAR __builtin_amdgcn_s_barrier()
;     __device__ __forceinline__ void operator()(f32x4 (&acc)[2][2][4][2], const Unit& u, int wr, int wc, int fr, int fq) const {
;     ...
;             for (int m = 0; m < 4; ++m) { const int row = row0 + ai * HALF + m * 16; float* orow = out + (size_t)row * DM + col0;
;                 const unsigned long long* sp = (const unsigned long long*)(xbuf + (size_t)row * 16 + 4 * fq);
;                 const unsigned long long qa = __hip_atomic_load(sp, __ATOMIC_RELAXED, __HIP_MEMORY_SCOPE_AGENT), qb = __hip_atomic_load(sp + 1, __ATOMIC_RELAXED, __HIP_MEMORY_SCOPE_AGENT);
;                 float t = (__uint_as_float((unsigned)qa) + __uint_as_float((unsigned)(qa >> 32))) + (__uint_as_float((unsigned)qb) + __uint_as_float((unsigned)(qb >> 32)));
;                 t += __shfl_xor(t, 16); t += __shfl_xor(t, 32);
;                 const float rs = rsqrtf(t * (1.0f / DM) + EPS);
; #pragma unroll
;                 for (int bj = 0; bj < 2; ++bj)
; #pragma unroll
;                     for (int n = 0; n < 2; ++n) { const int co = bj * HALF + n * 16; const f32x4 g = *(const f32x4*)(gf + col0 + co); *(f32x4*)(orow + co) = acc[ai][bj][m][n] * rs * g; } }
; template <class Epi, class SchedT, bool ALIGN_EPI, bool SP2, bool FP8 = false>
; __device__ __forceinline__ void gemm_phase(LAS unsigned char* lds, const Gemm g, const SchedT& S, const Epi& E, const int wid) {
;     ...
;         if (!has_next) break;
; #pragma unroll
;         for (int a = 0; a < 2; ++a)
; #pragma unroll
;             for (int b = 0; b < 2; ++b)
; #pragma unroll
;                 for (int m = 0; m < 4; ++m)
; #pragma unroll
;                     for (int n = 0; n < 2; ++n) acc[a][b][m][n] = (f32x4){0.f, 0.f, 0.f, 0.f};
;         cur = nxt; cA = nA; cB = nB; ++ui;
;         if constexpr (ALIGN_EPI) { if (wr == 1) PG8_BAR; }
	v_add_f32_e32 v54, v54, v55
	s_waitcnt vmcnt(0)
	v_add_f32_e32 v55, v56, v57
	v_add_f32_e32 v54, v54, v55
	ds_bpermute_b32 v55, v128, v54
	s_waitcnt lgkmcnt(0)
	v_add_f32_e32 v54, v54, v55
	ds_bpermute_b32 v55, v184, v54
	s_waitcnt lgkmcnt(0)
	v_add_f32_e32 v54, v54, v55
	v_fmamk_f32 v54, v54, 0x3a800000, v183
	s_nop 1
	v_rsq_f32_e32 v54, v54
	s_nop 0
	v_pk_mul_f32 v[56:57], v[158:159], v[54:55] op_sel_hi:[1,0]
	v_pk_mul_f32 v[46:47], v[46:47], v[54:55] op_sel_hi:[1,0]
	v_pk_mul_f32 v[48:49], v[48:49], v[56:57]
	v_pk_mul_f32 v[50:51], v[50:51], v[46:47]
	global_store_dwordx4 v[52:53], v[48:51], off
	s_nop 1
	v_mov_b64_e32 v[46:47], v[216:217]
	v_mov_b64_e32 v[48:49], v[218:219]
	v_pk_mul_f32 v[34:35], v[34:35], v[54:55] op_sel_hi:[1,0]
	v_pk_mul_f32 v[50:51], v[42:43], v[54:55] op_sel_hi:[1,0]
	v_pk_mul_f32 v[42:43], v[44:45], v[54:55] op_sel_hi:[1,0]
	v_pk_mul_f32 v[32:33], v[32:33], v[54:55] op_sel_hi:[1,0]
	v_pk_mul_f32 v[42:43], v[46:47], v[42:43]
	v_pk_mul_f32 v[44:45], v[48:49], v[50:51]
	global_store_dwordx4 v[52:53], v[42:45], off offset:64
	s_nop 1
	v_mov_b64_e32 v[42:43], v[220:221]
	v_mov_b64_e32 v[44:45], v[222:223]
	v_pk_mul_f32 v[46:47], v[38:39], v[54:55] op_sel_hi:[1,0]
	v_pk_mul_f32 v[38:39], v[40:41], v[54:55] op_sel_hi:[1,0]
	v_pk_mul_f32 v[40:41], v[44:45], v[46:47]
	v_pk_mul_f32 v[38:39], v[42:43], v[38:39]
	global_store_dwordx4 v[52:53], v[38:41], off offset:512
	s_nop 1
	v_mov_b64_e32 v[38:39], v[224:225]
	v_mov_b64_e32 v[40:41], v[226:227]
	v_lshl_add_u64 v[42:43], v[166:167], 0, v[170:171]
	v_pk_mul_f32 v[32:33], v[38:39], v[32:33]
	v_pk_mul_f32 v[34:35], v[40:41], v[34:35]
	global_store_dwordx4 v[52:53], v[32:35], off offset:576
	global_load_dwordx2 v[38:39], v[42:43], off sc1
	global_load_dwordx2 v[40:41], v[42:43], off offset:8 sc1
	s_nop 0
	s_nop 1
	v_mov_b64_e32 v[32:33], v[212:213]
	v_mov_b64_e32 v[34:35], v[214:215]
	s_waitcnt vmcnt(1)
	v_add_f32_e32 v38, v38, v39
	s_waitcnt vmcnt(0)
	v_add_f32_e32 v39, v40, v41
	v_add_f32_e32 v38, v38, v39
	ds_bpermute_b32 v39, v128, v38
	s_waitcnt lgkmcnt(0)
	v_add_f32_e32 v38, v38, v39
	ds_bpermute_b32 v39, v184, v38
	s_waitcnt lgkmcnt(0)
	v_add_f32_e32 v38, v38, v39
	v_fmamk_f32 v38, v38, 0x3a800000, v183
	s_nop 1
	v_rsq_f32_e32 v38, v38
	s_nop 0
	v_pk_mul_f32 v[40:41], v[162:163], v[38:39] op_sel_hi:[1,0]
	v_pk_mul_f32 v[30:31], v[30:31], v[38:39] op_sel_hi:[1,0]
	v_pk_mul_f32 v[32:33], v[32:33], v[40:41]
	v_pk_mul_f32 v[34:35], v[34:35], v[30:31]
	global_store_dwordx4 v[36:37], v[32:35], off
	s_nop 1
	v_mov_b64_e32 v[30:31], v[216:217]
	v_mov_b64_e32 v[32:33], v[218:219]
	v_pk_mul_f32 v[18:19], v[18:19], v[38:39] op_sel_hi:[1,0]
	v_pk_mul_f32 v[34:35], v[26:27], v[38:39] op_sel_hi:[1,0]
	v_pk_mul_f32 v[26:27], v[28:29], v[38:39] op_sel_hi:[1,0]
	v_pk_mul_f32 v[16:17], v[16:17], v[38:39] op_sel_hi:[1,0]
	v_pk_mul_f32 v[26:27], v[30:31], v[26:27]
	v_pk_mul_f32 v[28:29], v[32:33], v[34:35]
	global_store_dwordx4 v[36:37], v[26:29], off offset:64
	s_nop 1
	v_mov_b64_e32 v[26:27], v[220:221]
	v_mov_b64_e32 v[28:29], v[222:223]
	v_pk_mul_f32 v[30:31], v[22:23], v[38:39] op_sel_hi:[1,0]
	v_pk_mul_f32 v[22:23], v[24:25], v[38:39] op_sel_hi:[1,0]
	v_pk_mul_f32 v[24:25], v[28:29], v[30:31]
	v_pk_mul_f32 v[22:23], v[26:27], v[22:23]
	global_store_dwordx4 v[36:37], v[22:25], off offset:512
	s_nop 1
	v_mov_b64_e32 v[22:23], v[224:225]
	v_mov_b64_e32 v[24:25], v[226:227]
	v_lshl_add_u64 v[26:27], v[168:169], 0, v[170:171]
	v_pk_mul_f32 v[16:17], v[22:23], v[16:17]
	v_pk_mul_f32 v[18:19], v[24:25], v[18:19]
	global_store_dwordx4 v[36:37], v[16:19], off offset:576
	global_load_dwordx2 v[22:23], v[26:27], off sc1
	global_load_dwordx2 v[24:25], v[26:27], off offset:8 sc1
	s_nop 0
	s_nop 1
	v_mov_b64_e32 v[16:17], v[212:213]
	v_mov_b64_e32 v[18:19], v[214:215]
	s_waitcnt vmcnt(1)
	v_add_f32_e32 v22, v22, v23
	s_waitcnt vmcnt(0)
	v_add_f32_e32 v23, v24, v25
	v_add_f32_e32 v22, v22, v23
	ds_bpermute_b32 v23, v128, v22
	s_waitcnt lgkmcnt(0)
	v_add_f32_e32 v22, v22, v23
	ds_bpermute_b32 v23, v184, v22
	s_waitcnt lgkmcnt(0)
	v_add_f32_e32 v22, v22, v23
	v_fmamk_f32 v22, v22, 0x3a800000, v183
	s_nop 1
	v_rsq_f32_e32 v22, v22
	s_nop 0
	v_pk_mul_f32 v[12:13], v[12:13], v[22:23] op_sel_hi:[1,0]
	v_pk_mul_f32 v[14:15], v[14:15], v[22:23] op_sel_hi:[1,0]
	v_pk_mul_f32 v[12:13], v[16:17], v[12:13]
	v_pk_mul_f32 v[14:15], v[18:19], v[14:15]
	global_store_dwordx4 v[20:21], v[12:15], off
	s_nop 1
	v_mov_b64_e32 v[12:13], v[216:217]
	v_mov_b64_e32 v[14:15], v[218:219]
	v_pk_mul_f32 v[10:11], v[10:11], v[22:23] op_sel_hi:[1,0]
	v_pk_mul_f32 v[8:9], v[8:9], v[22:23] op_sel_hi:[1,0]
	v_pk_mul_f32 v[6:7], v[6:7], v[22:23] op_sel_hi:[1,0]
	v_pk_mul_f32 v[4:5], v[4:5], v[22:23] op_sel_hi:[1,0]
	v_pk_mul_f32 v[2:3], v[2:3], v[22:23] op_sel_hi:[1,0]
	v_pk_mul_f32 v[0:1], v[0:1], v[22:23] op_sel_hi:[1,0]
	s_andn2_b64 vcc, exec, s[4:5]
	s_mov_b64 s[4:5], -1
	v_pk_mul_f32 v[8:9], v[12:13], v[8:9]
	v_pk_mul_f32 v[10:11], v[14:15], v[10:11]
	global_store_dwordx4 v[20:21], v[8:11], off offset:64
	s_nop 1
	v_mov_b64_e32 v[8:9], v[220:221]
	v_mov_b64_e32 v[10:11], v[222:223]
	v_pk_mul_f32 v[4:5], v[8:9], v[4:5]
	v_pk_mul_f32 v[6:7], v[10:11], v[6:7]
	global_store_dwordx4 v[20:21], v[4:7], off offset:512
	s_nop 1
	v_mov_b64_e32 v[4:5], v[224:225]
	v_mov_b64_e32 v[6:7], v[226:227]
	v_pk_mul_f32 v[0:1], v[4:5], v[0:1]
	v_pk_mul_f32 v[2:3], v[6:7], v[2:3]
	global_store_dwordx4 v[20:21], v[0:3], off offset:576
	s_cbranch_vccnz .LBB0_965
	s_and_b64 vcc, exec, s[0:1]
	s_cbranch_vccnz .LBB0_964
	s_barrier
	s_branch .LBB0_964
